# C-D grid barrier: the early-arriving non-SSD half writes back its L2 on arrival (off the critical path); also one-batch x-conv weight staging in SSD setup
# baseline (speedup 1.0000x reference)
; __device__ __forceinline__ int lane_fresh() { int l; asm volatile("v_mbcnt_lo_u32_b32 %0, -1, 0\n\tv_mbcnt_hi_u32_b32 %0, -1, %0" : "=v"(l)); return l; }
; #define LAS __attribute__((address_space(3)))
; __device__ __forceinline__ unsigned xb_xcc_id() { return (unsigned)__builtin_amdgcn_s_getreg((3 << 11) | 20) & 0xFu; }
; __device__ __forceinline__ void xcd_barrier(unsigned* bar, const int wv) {
;   asm volatile("s_waitcnt vmcnt(0)" ::: "memory");
;   __syncthreads();
;   if (wv == 0) {
;     if (lane_fresh() == 0) {
;       volatile LAS unsigned* st = (volatile LAS unsigned*)&xb_words;
;       const unsigned x = xb_xcc_id();
;       __builtin_amdgcn_s_waitcnt(0);
;       unsigned nloc = st[0], nx = st[1];
;       if (nloc == 0u) { xcd_barrier_complete(bar, x, nloc, nx); st[0] = nloc; st[1] = nx; }
.LBB0_633:
	s_waitcnt vmcnt(0)
	v_readlane_b32 s0, v251, 58
	v_readlane_b32 s1, v251, 59
	s_and_b64 vcc, exec, s[0:1]
	s_mov_b32 s33, 1
	s_waitcnt lgkmcnt(0)
	s_barrier
	s_cbranch_vccnz .LBB0_687
	v_readlane_b32 s2, v251, 0
	v_readlane_b32 s3, v251, 1
	s_lshr_b32 s3, s3, 1
	s_cmp_lt_u32 s2, s3
	s_cbranch_scc1 .Lcd_noflush
	buffer_wbl2 sc1
	s_waitcnt vmcnt(0)
.Lcd_noflush:
	v_mbcnt_lo_u32_b32 v0, -1, 0
	v_mbcnt_hi_u32_b32 v0, -1, v0
	s_nop 0
	v_cmp_eq_u32_e32 vcc, 0, v0
	s_and_saveexec_b64 s[0:1], vcc
	s_cbranch_execz .LBB0_686
	v_mov_b32_e32 v0, 0
	s_getreg_b32 s2, hwreg(HW_REG_XCC_ID, 0, 4)
	s_waitcnt vmcnt(0) expcnt(0) lgkmcnt(0)
	ds_read_b32 v2, v0
	ds_read_b32 v1, v0 offset:4
	s_and_b32 s44, s2, 15
	s_waitcnt lgkmcnt(1)
	v_cmp_ne_u32_e32 vcc, 0, v2
	s_cbranch_vccnz .LBB0_650
	s_add_u32 s2, s50, 0x12416200
	s_addc_u32 s3, s51, 0
	s_add_u32 s4, s50, 0x12416400
	s_addc_u32 s5, s51, 0
	s_add_u32 s6, s50, 0x12416500
	s_addc_u32 s7, s51, 0
	s_add_u32 s8, s50, 0x12416600
	s_addc_u32 s9, s51, 0
	s_add_u32 s10, s50, 0x12416700
	s_addc_u32 s11, s51, 0
	s_add_u32 s12, s50, 0x12416800
	s_addc_u32 s13, s51, 0
	s_add_u32 s14, s50, 0x12416900
	s_addc_u32 s15, s51, 0
	s_add_u32 s16, s50, 0x12416a00
	s_addc_u32 s17, s51, 0
	s_add_u32 s18, s50, 0x12416b00
	s_addc_u32 s19, s51, 0
	s_add_u32 s20, s50, 0x12416c00
	s_addc_u32 s21, s51, 0
	s_add_u32 s22, s50, 0x12416d00
	s_addc_u32 s23, s51, 0
	s_add_u32 s24, s50, 0x12416e00
	s_addc_u32 s25, s51, 0
	s_add_u32 s26, s50, 0x12416f00
	s_addc_u32 s27, s51, 0
	s_add_u32 s28, s50, 0x12417000
	s_addc_u32 s29, s51, 0
	s_add_u32 s30, s50, 0x12417100
	s_addc_u32 s31, s51, 0
	s_add_u32 s34, s50, 0x12417200
	s_addc_u32 s35, s51, 0
	s_add_u32 s36, s50, 0x12417300
	s_addc_u32 s37, s51, 0
	s_mov_b32 s45, 1
	s_branch .LBB0_638
